# v119: final-norm row parts read the mixer output rows with the default cache policy (same-XCD producers, L2 hits) instead of sc1
# baseline (speedup 1.0000x reference)
.Lp45_ready:
	s_barrier
	s_lshl_b32 s66, s64, 8
	s_and_b32 s67, s84, 3
	s_lshl_b32 s67, s67, 6
	s_add_i32 s66, s66, s67
	s_lshl_b32 s67, s74, 3
	s_add_i32 s66, s66, s67
	s_cmp_lt_u32 s66, 0x8000
	s_cselect_b32 s52, s12, s14
	s_cselect_b32 s53, s13, s15
	s_cselect_b32 s67, 0, 0x8000
	s_sub_u32 s67, s66, s67
	s_lshl_b32 s67, s67, 12
	s_add_u32 s52, s52, s67
	s_addc_u32 s53, s53, 0
	v_readlane_b32 s54, v254, 22
	v_readlane_b32 s55, v254, 23
	s_lshl_b32 s67, s66, 11
	s_add_u32 s54, s54, s67
	s_addc_u32 s55, s55, 0
	s_lshl_b32 s67, s66, 12
	s_add_u32 s56, s40, s67
	s_addc_u32 s57, s41, 0
	v_mov_b32_e32 v124, 0x358637bd
	global_load_dwordx4 v[196:199], v194, s[38:39] offset:0
	global_load_dwordx4 v[200:203], v194, s[38:39] offset:1024
	global_load_dwordx4 v[204:207], v194, s[38:39] offset:2048
	global_load_dwordx4 v[208:211], v194, s[38:39] offset:3072
	s_mov_b64 s[2:3], s[52:53]
	s_mov_b64 s[44:45], s[56:57]
	s_mov_b64 s[26:27], s[54:55]
	global_load_dwordx2 v[82:83], v188, s[26:27] offset:0
	global_load_dwordx2 v[84:85], v188, s[26:27] offset:512
	global_load_dwordx2 v[86:87], v188, s[26:27] offset:1024
	global_load_dwordx2 v[88:89], v188, s[26:27] offset:1536
	global_load_dwordx4 v[18:21], v194, s[2:3] offset:0 nt
	global_load_dwordx4 v[22:25], v194, s[2:3] offset:1024 nt
	global_load_dwordx4 v[26:29], v194, s[2:3] offset:2048 nt
	global_load_dwordx4 v[30:33], v194, s[2:3] offset:3072 nt
	s_add_u32 s4, s52, 0x1000
	s_addc_u32 s5, s53, 0
	s_add_u32 s46, s56, 0x1000
	s_addc_u32 s47, s57, 0
	s_add_u32 s28, s54, 0x800
	s_addc_u32 s29, s55, 0
	global_load_dwordx2 v[90:91], v188, s[28:29] offset:0
	global_load_dwordx2 v[92:93], v188, s[28:29] offset:512
	global_load_dwordx2 v[94:95], v188, s[28:29] offset:1024
	global_load_dwordx2 v[96:97], v188, s[28:29] offset:1536
	global_load_dwordx4 v[34:37], v194, s[4:5] offset:0 nt
	global_load_dwordx4 v[38:41], v194, s[4:5] offset:1024 nt
	global_load_dwordx4 v[42:45], v194, s[4:5] offset:2048 nt
	global_load_dwordx4 v[46:49], v194, s[4:5] offset:3072 nt
	s_add_u32 s6, s52, 0x2000
	s_addc_u32 s7, s53, 0
	s_add_u32 s48, s56, 0x2000
	s_addc_u32 s49, s57, 0
	s_add_u32 s30, s54, 0x1000
	s_addc_u32 s31, s55, 0
	global_load_dwordx2 v[98:99], v188, s[30:31] offset:0
	global_load_dwordx2 v[100:101], v188, s[30:31] offset:512
	global_load_dwordx2 v[102:103], v188, s[30:31] offset:1024
	global_load_dwordx2 v[104:105], v188, s[30:31] offset:1536
	global_load_dwordx4 v[50:53], v194, s[6:7] offset:0 nt
	global_load_dwordx4 v[54:57], v194, s[6:7] offset:1024 nt
	global_load_dwordx4 v[58:61], v194, s[6:7] offset:2048 nt
	global_load_dwordx4 v[62:65], v194, s[6:7] offset:3072 nt
	s_add_u32 s8, s52, 0x3000
	s_addc_u32 s9, s53, 0
	s_add_u32 s50, s56, 0x3000
	s_addc_u32 s51, s57, 0
	s_add_u32 s34, s54, 0x1800
	s_addc_u32 s35, s55, 0
	global_load_dwordx2 v[106:107], v188, s[34:35] offset:0
	global_load_dwordx2 v[108:109], v188, s[34:35] offset:512
	global_load_dwordx2 v[110:111], v188, s[34:35] offset:1024
	global_load_dwordx2 v[112:113], v188, s[34:35] offset:1536
	global_load_dwordx4 v[66:69], v194, s[8:9] offset:0 nt
	global_load_dwordx4 v[70:73], v194, s[8:9] offset:1024 nt
	global_load_dwordx4 v[74:77], v194, s[8:9] offset:2048 nt
	global_load_dwordx4 v[78:81], v194, s[8:9] offset:3072 nt
	s_waitcnt vmcnt(24)
	v_lshlrev_b32_e32 v118, 16, v82
	v_and_b32_e32 v119, 0xffff0000, v82
	v_lshlrev_b32_e32 v120, 16, v83
	v_and_b32_e32 v121, 0xffff0000, v83
	v_add_f32_e32 v18, v18, v118
	v_add_f32_e32 v19, v19, v119
	v_add_f32_e32 v20, v20, v120
	v_add_f32_e32 v21, v21, v121
	v_lshlrev_b32_e32 v118, 16, v84
	v_and_b32_e32 v119, 0xffff0000, v84
	v_lshlrev_b32_e32 v120, 16, v85
	v_and_b32_e32 v121, 0xffff0000, v85
	v_add_f32_e32 v22, v22, v118
	v_add_f32_e32 v23, v23, v119
	v_add_f32_e32 v24, v24, v120
	v_add_f32_e32 v25, v25, v121
	v_lshlrev_b32_e32 v118, 16, v86
	v_and_b32_e32 v119, 0xffff0000, v86
	v_lshlrev_b32_e32 v120, 16, v87
	v_and_b32_e32 v121, 0xffff0000, v87
	v_add_f32_e32 v26, v26, v118
	v_add_f32_e32 v27, v27, v119
	v_add_f32_e32 v28, v28, v120
	v_add_f32_e32 v29, v29, v121
	v_lshlrev_b32_e32 v118, 16, v88
	v_and_b32_e32 v119, 0xffff0000, v88
	v_lshlrev_b32_e32 v120, 16, v89
	v_and_b32_e32 v121, 0xffff0000, v89
	v_add_f32_e32 v30, v30, v118
	v_add_f32_e32 v31, v31, v119
	v_add_f32_e32 v32, v32, v120
	v_add_f32_e32 v33, v33, v121
	v_mul_f32_e32 v114, v18, v18
	v_fmac_f32_e32 v114, v19, v19
	v_fmac_f32_e32 v114, v20, v20
	v_fmac_f32_e32 v114, v21, v21
	v_fmac_f32_e32 v114, v22, v22
	v_fmac_f32_e32 v114, v23, v23
	v_fmac_f32_e32 v114, v24, v24
	v_fmac_f32_e32 v114, v25, v25
	v_fmac_f32_e32 v114, v26, v26
	v_fmac_f32_e32 v114, v27, v27
	v_fmac_f32_e32 v114, v28, v28
	v_fmac_f32_e32 v114, v29, v29
	v_fmac_f32_e32 v114, v30, v30
	v_fmac_f32_e32 v114, v31, v31
	v_fmac_f32_e32 v114, v32, v32
	v_fmac_f32_e32 v114, v33, v33
	ds_bpermute_b32 v115, v142, v114
	s_waitcnt lgkmcnt(0)
	v_add_f32_e32 v114, v114, v115
	ds_bpermute_b32 v115, v143, v114
	s_waitcnt lgkmcnt(0)
	v_add_f32_e32 v114, v114, v115
	ds_bpermute_b32 v115, v144, v114
	s_waitcnt lgkmcnt(0)
	v_add_f32_e32 v114, v114, v115
	ds_bpermute_b32 v115, v145, v114
	s_waitcnt lgkmcnt(0)
	v_add_f32_e32 v114, v114, v115
	ds_bpermute_b32 v115, v146, v114
	s_waitcnt lgkmcnt(0)
	v_add_f32_e32 v114, v114, v115
	ds_bpermute_b32 v115, v147, v114
	s_waitcnt lgkmcnt(0)
	v_add_f32_e32 v114, v114, v115
	v_fmamk_f32 v114, v114, 0x3a800000, v124
	v_rsq_f32_e32 v116, v114
	s_nop 0
	v_mul_f32_e32 v118, v116, v196
	v_mul_f32_e32 v18, v18, v118
	v_mul_f32_e32 v119, v116, v197
	v_mul_f32_e32 v19, v19, v119
	v_mul_f32_e32 v120, v116, v198
	v_mul_f32_e32 v20, v20, v120
	v_mul_f32_e32 v121, v116, v199
	v_mul_f32_e32 v21, v21, v121
	global_store_dwordx4 v194, v[18:21], s[44:45] offset:0
	v_mul_f32_e32 v118, v116, v200
	v_mul_f32_e32 v22, v22, v118
	v_mul_f32_e32 v119, v116, v201
	v_mul_f32_e32 v23, v23, v119
	v_mul_f32_e32 v120, v116, v202
	v_mul_f32_e32 v24, v24, v120
	v_mul_f32_e32 v121, v116, v203
	v_mul_f32_e32 v25, v25, v121
	global_store_dwordx4 v194, v[22:25], s[44:45] offset:1024
	v_mul_f32_e32 v118, v116, v204
	v_mul_f32_e32 v26, v26, v118
	v_mul_f32_e32 v119, v116, v205
	v_mul_f32_e32 v27, v27, v119
	v_mul_f32_e32 v120, v116, v206
	v_mul_f32_e32 v28, v28, v120
	v_mul_f32_e32 v121, v116, v207
	v_mul_f32_e32 v29, v29, v121
	global_store_dwordx4 v194, v[26:29], s[44:45] offset:2048
	v_mul_f32_e32 v118, v116, v208
	v_mul_f32_e32 v30, v30, v118
	v_mul_f32_e32 v119, v116, v209
	v_mul_f32_e32 v31, v31, v119
	v_mul_f32_e32 v120, v116, v210
	v_mul_f32_e32 v32, v32, v120
	v_mul_f32_e32 v121, v116, v211
	v_mul_f32_e32 v33, v33, v121
	global_store_dwordx4 v194, v[30:33], s[44:45] offset:3072
	s_add_u32 s2, s52, 0x4000
	s_addc_u32 s3, s53, 0
	s_add_u32 s44, s56, 0x4000
	s_addc_u32 s45, s57, 0
	s_add_u32 s26, s54, 0x2000
	s_addc_u32 s27, s55, 0
	global_load_dwordx2 v[82:83], v188, s[26:27] offset:0
	global_load_dwordx2 v[84:85], v188, s[26:27] offset:512
	global_load_dwordx2 v[86:87], v188, s[26:27] offset:1024
	global_load_dwordx2 v[88:89], v188, s[26:27] offset:1536
	global_load_dwordx4 v[18:21], v194, s[2:3] offset:0 nt
	global_load_dwordx4 v[22:25], v194, s[2:3] offset:1024 nt
	global_load_dwordx4 v[26:29], v194, s[2:3] offset:2048 nt
	global_load_dwordx4 v[30:33], v194, s[2:3] offset:3072 nt
	s_waitcnt vmcnt(28)
	v_lshlrev_b32_e32 v118, 16, v90
	v_and_b32_e32 v119, 0xffff0000, v90
	v_lshlrev_b32_e32 v120, 16, v91
	v_and_b32_e32 v121, 0xffff0000, v91
	v_add_f32_e32 v34, v34, v118
	v_add_f32_e32 v35, v35, v119
	v_add_f32_e32 v36, v36, v120
	v_add_f32_e32 v37, v37, v121
	v_lshlrev_b32_e32 v118, 16, v92
	v_and_b32_e32 v119, 0xffff0000, v92
	v_lshlrev_b32_e32 v120, 16, v93
	v_and_b32_e32 v121, 0xffff0000, v93
	v_add_f32_e32 v38, v38, v118
	v_add_f32_e32 v39, v39, v119
	v_add_f32_e32 v40, v40, v120
	v_add_f32_e32 v41, v41, v121
	v_lshlrev_b32_e32 v118, 16, v94
	v_and_b32_e32 v119, 0xffff0000, v94
	v_lshlrev_b32_e32 v120, 16, v95
	v_and_b32_e32 v121, 0xffff0000, v95
	v_add_f32_e32 v42, v42, v118
	v_add_f32_e32 v43, v43, v119
	v_add_f32_e32 v44, v44, v120
	v_add_f32_e32 v45, v45, v121
	v_lshlrev_b32_e32 v118, 16, v96
	v_and_b32_e32 v119, 0xffff0000, v96
	v_lshlrev_b32_e32 v120, 16, v97
	v_and_b32_e32 v121, 0xffff0000, v97
	v_add_f32_e32 v46, v46, v118
	v_add_f32_e32 v47, v47, v119
	v_add_f32_e32 v48, v48, v120
	v_add_f32_e32 v49, v49, v121
	v_mul_f32_e32 v114, v34, v34
	v_fmac_f32_e32 v114, v35, v35
	v_fmac_f32_e32 v114, v36, v36
	v_fmac_f32_e32 v114, v37, v37
	v_fmac_f32_e32 v114, v38, v38
	v_fmac_f32_e32 v114, v39, v39
	v_fmac_f32_e32 v114, v40, v40
	v_fmac_f32_e32 v114, v41, v41
	v_fmac_f32_e32 v114, v42, v42
	v_fmac_f32_e32 v114, v43, v43
	v_fmac_f32_e32 v114, v44, v44
	v_fmac_f32_e32 v114, v45, v45
	v_fmac_f32_e32 v114, v46, v46
	v_fmac_f32_e32 v114, v47, v47
	v_fmac_f32_e32 v114, v48, v48
	v_fmac_f32_e32 v114, v49, v49
	ds_bpermute_b32 v115, v142, v114
	s_waitcnt lgkmcnt(0)
	v_add_f32_e32 v114, v114, v115
	ds_bpermute_b32 v115, v143, v114
	s_waitcnt lgkmcnt(0)
	v_add_f32_e32 v114, v114, v115
	ds_bpermute_b32 v115, v144, v114
	s_waitcnt lgkmcnt(0)
	v_add_f32_e32 v114, v114, v115
	ds_bpermute_b32 v115, v145, v114
	s_waitcnt lgkmcnt(0)
	v_add_f32_e32 v114, v114, v115
	ds_bpermute_b32 v115, v146, v114
	s_waitcnt lgkmcnt(0)
	v_add_f32_e32 v114, v114, v115
	ds_bpermute_b32 v115, v147, v114
	s_waitcnt lgkmcnt(0)
	v_add_f32_e32 v114, v114, v115
	v_fmamk_f32 v114, v114, 0x3a800000, v124
	v_rsq_f32_e32 v116, v114
	s_nop 0
	v_mul_f32_e32 v118, v116, v196
	v_mul_f32_e32 v34, v34, v118
	v_mul_f32_e32 v119, v116, v197
	v_mul_f32_e32 v35, v35, v119
	v_mul_f32_e32 v120, v116, v198
	v_mul_f32_e32 v36, v36, v120
	v_mul_f32_e32 v121, v116, v199
	v_mul_f32_e32 v37, v37, v121
	global_store_dwordx4 v194, v[34:37], s[46:47] offset:0
	v_mul_f32_e32 v118, v116, v200
	v_mul_f32_e32 v38, v38, v118
	v_mul_f32_e32 v119, v116, v201
	v_mul_f32_e32 v39, v39, v119
	v_mul_f32_e32 v120, v116, v202
	v_mul_f32_e32 v40, v40, v120
	v_mul_f32_e32 v121, v116, v203
	v_mul_f32_e32 v41, v41, v121
	global_store_dwordx4 v194, v[38:41], s[46:47] offset:1024
	v_mul_f32_e32 v118, v116, v204
	v_mul_f32_e32 v42, v42, v118
	v_mul_f32_e32 v119, v116, v205
	v_mul_f32_e32 v43, v43, v119
	v_mul_f32_e32 v120, v116, v206
	v_mul_f32_e32 v44, v44, v120
	v_mul_f32_e32 v121, v116, v207
	v_mul_f32_e32 v45, v45, v121
	global_store_dwordx4 v194, v[42:45], s[46:47] offset:2048
	v_mul_f32_e32 v118, v116, v208
	v_mul_f32_e32 v46, v46, v118
	v_mul_f32_e32 v119, v116, v209
	v_mul_f32_e32 v47, v47, v119
	v_mul_f32_e32 v120, v116, v210
	v_mul_f32_e32 v48, v48, v120
	v_mul_f32_e32 v121, v116, v211
	v_mul_f32_e32 v49, v49, v121
	global_store_dwordx4 v194, v[46:49], s[46:47] offset:3072
	s_add_u32 s4, s52, 0x5000
	s_addc_u32 s5, s53, 0
	s_add_u32 s46, s56, 0x5000
	s_addc_u32 s47, s57, 0
	s_add_u32 s28, s54, 0x2800
	s_addc_u32 s29, s55, 0
	global_load_dwordx2 v[90:91], v188, s[28:29] offset:0
	global_load_dwordx2 v[92:93], v188, s[28:29] offset:512
	global_load_dwordx2 v[94:95], v188, s[28:29] offset:1024
	global_load_dwordx2 v[96:97], v188, s[28:29] offset:1536
	global_load_dwordx4 v[34:37], v194, s[4:5] offset:0 nt
	global_load_dwordx4 v[38:41], v194, s[4:5] offset:1024 nt
	global_load_dwordx4 v[42:45], v194, s[4:5] offset:2048 nt
	global_load_dwordx4 v[46:49], v194, s[4:5] offset:3072 nt
	s_waitcnt vmcnt(32)
	v_lshlrev_b32_e32 v118, 16, v98
	v_and_b32_e32 v119, 0xffff0000, v98
	v_lshlrev_b32_e32 v120, 16, v99
	v_and_b32_e32 v121, 0xffff0000, v99
	v_add_f32_e32 v50, v50, v118
	v_add_f32_e32 v51, v51, v119
	v_add_f32_e32 v52, v52, v120
	v_add_f32_e32 v53, v53, v121
	v_lshlrev_b32_e32 v118, 16, v100
	v_and_b32_e32 v119, 0xffff0000, v100
	v_lshlrev_b32_e32 v120, 16, v101
	v_and_b32_e32 v121, 0xffff0000, v101
	v_add_f32_e32 v54, v54, v118
	v_add_f32_e32 v55, v55, v119
	v_add_f32_e32 v56, v56, v120
	v_add_f32_e32 v57, v57, v121
	v_lshlrev_b32_e32 v118, 16, v102
	v_and_b32_e32 v119, 0xffff0000, v102
	v_lshlrev_b32_e32 v120, 16, v103
	v_and_b32_e32 v121, 0xffff0000, v103
	v_add_f32_e32 v58, v58, v118
	v_add_f32_e32 v59, v59, v119
	v_add_f32_e32 v60, v60, v120
	v_add_f32_e32 v61, v61, v121
	v_lshlrev_b32_e32 v118, 16, v104
	v_and_b32_e32 v119, 0xffff0000, v104
	v_lshlrev_b32_e32 v120, 16, v105
	v_and_b32_e32 v121, 0xffff0000, v105
	v_add_f32_e32 v62, v62, v118
	v_add_f32_e32 v63, v63, v119
	v_add_f32_e32 v64, v64, v120
	v_add_f32_e32 v65, v65, v121
	v_mul_f32_e32 v114, v50, v50
	v_fmac_f32_e32 v114, v51, v51
	v_fmac_f32_e32 v114, v52, v52
	v_fmac_f32_e32 v114, v53, v53
	v_fmac_f32_e32 v114, v54, v54
	v_fmac_f32_e32 v114, v55, v55
	v_fmac_f32_e32 v114, v56, v56
	v_fmac_f32_e32 v114, v57, v57
	v_fmac_f32_e32 v114, v58, v58
	v_fmac_f32_e32 v114, v59, v59
	v_fmac_f32_e32 v114, v60, v60
	v_fmac_f32_e32 v114, v61, v61
	v_fmac_f32_e32 v114, v62, v62
	v_fmac_f32_e32 v114, v63, v63
	v_fmac_f32_e32 v114, v64, v64
	v_fmac_f32_e32 v114, v65, v65
	ds_bpermute_b32 v115, v142, v114
	s_waitcnt lgkmcnt(0)
	v_add_f32_e32 v114, v114, v115
	ds_bpermute_b32 v115, v143, v114
	s_waitcnt lgkmcnt(0)
	v_add_f32_e32 v114, v114, v115
	ds_bpermute_b32 v115, v144, v114
	s_waitcnt lgkmcnt(0)
	v_add_f32_e32 v114, v114, v115
	ds_bpermute_b32 v115, v145, v114
	s_waitcnt lgkmcnt(0)
	v_add_f32_e32 v114, v114, v115
	ds_bpermute_b32 v115, v146, v114
	s_waitcnt lgkmcnt(0)
	v_add_f32_e32 v114, v114, v115
	ds_bpermute_b32 v115, v147, v114
	s_waitcnt lgkmcnt(0)
	v_add_f32_e32 v114, v114, v115
	v_fmamk_f32 v114, v114, 0x3a800000, v124
	v_rsq_f32_e32 v116, v114
	s_nop 0
	v_mul_f32_e32 v118, v116, v196
	v_mul_f32_e32 v50, v50, v118
	v_mul_f32_e32 v119, v116, v197
	v_mul_f32_e32 v51, v51, v119
	v_mul_f32_e32 v120, v116, v198
	v_mul_f32_e32 v52, v52, v120
	v_mul_f32_e32 v121, v116, v199
	v_mul_f32_e32 v53, v53, v121
	global_store_dwordx4 v194, v[50:53], s[48:49] offset:0
	v_mul_f32_e32 v118, v116, v200
	v_mul_f32_e32 v54, v54, v118
	v_mul_f32_e32 v119, v116, v201
	v_mul_f32_e32 v55, v55, v119
	v_mul_f32_e32 v120, v116, v202
	v_mul_f32_e32 v56, v56, v120
	v_mul_f32_e32 v121, v116, v203
	v_mul_f32_e32 v57, v57, v121
	global_store_dwordx4 v194, v[54:57], s[48:49] offset:1024
	v_mul_f32_e32 v118, v116, v204
	v_mul_f32_e32 v58, v58, v118
	v_mul_f32_e32 v119, v116, v205
	v_mul_f32_e32 v59, v59, v119
	v_mul_f32_e32 v120, v116, v206
	v_mul_f32_e32 v60, v60, v120
	v_mul_f32_e32 v121, v116, v207
	v_mul_f32_e32 v61, v61, v121
	global_store_dwordx4 v194, v[58:61], s[48:49] offset:2048
	v_mul_f32_e32 v118, v116, v208
	v_mul_f32_e32 v62, v62, v118
	v_mul_f32_e32 v119, v116, v209
	v_mul_f32_e32 v63, v63, v119
	v_mul_f32_e32 v120, v116, v210
	v_mul_f32_e32 v64, v64, v120
	v_mul_f32_e32 v121, v116, v211
	v_mul_f32_e32 v65, v65, v121
	global_store_dwordx4 v194, v[62:65], s[48:49] offset:3072
	s_add_u32 s6, s52, 0x6000
	s_addc_u32 s7, s53, 0
	s_add_u32 s48, s56, 0x6000
	s_addc_u32 s49, s57, 0
	s_add_u32 s30, s54, 0x3000
	s_addc_u32 s31, s55, 0
	global_load_dwordx2 v[98:99], v188, s[30:31] offset:0
	global_load_dwordx2 v[100:101], v188, s[30:31] offset:512
	global_load_dwordx2 v[102:103], v188, s[30:31] offset:1024
	global_load_dwordx2 v[104:105], v188, s[30:31] offset:1536
	global_load_dwordx4 v[50:53], v194, s[6:7] offset:0 nt
	global_load_dwordx4 v[54:57], v194, s[6:7] offset:1024 nt
	global_load_dwordx4 v[58:61], v194, s[6:7] offset:2048 nt
	global_load_dwordx4 v[62:65], v194, s[6:7] offset:3072 nt
	s_waitcnt vmcnt(36)
	v_lshlrev_b32_e32 v118, 16, v106
	v_and_b32_e32 v119, 0xffff0000, v106
	v_lshlrev_b32_e32 v120, 16, v107
	v_and_b32_e32 v121, 0xffff0000, v107
	v_add_f32_e32 v66, v66, v118
	v_add_f32_e32 v67, v67, v119
	v_add_f32_e32 v68, v68, v120
	v_add_f32_e32 v69, v69, v121
	v_lshlrev_b32_e32 v118, 16, v108
	v_and_b32_e32 v119, 0xffff0000, v108
	v_lshlrev_b32_e32 v120, 16, v109
	v_and_b32_e32 v121, 0xffff0000, v109
	v_add_f32_e32 v70, v70, v118
	v_add_f32_e32 v71, v71, v119
	v_add_f32_e32 v72, v72, v120
	v_add_f32_e32 v73, v73, v121
	v_lshlrev_b32_e32 v118, 16, v110
	v_and_b32_e32 v119, 0xffff0000, v110
	v_lshlrev_b32_e32 v120, 16, v111
	v_and_b32_e32 v121, 0xffff0000, v111
	v_add_f32_e32 v74, v74, v118
	v_add_f32_e32 v75, v75, v119
	v_add_f32_e32 v76, v76, v120
	v_add_f32_e32 v77, v77, v121
	v_lshlrev_b32_e32 v118, 16, v112
	v_and_b32_e32 v119, 0xffff0000, v112
	v_lshlrev_b32_e32 v120, 16, v113
	v_and_b32_e32 v121, 0xffff0000, v113
	v_add_f32_e32 v78, v78, v118
	v_add_f32_e32 v79, v79, v119
	v_add_f32_e32 v80, v80, v120
	v_add_f32_e32 v81, v81, v121
	v_mul_f32_e32 v114, v66, v66
	v_fmac_f32_e32 v114, v67, v67
	v_fmac_f32_e32 v114, v68, v68
	v_fmac_f32_e32 v114, v69, v69
	v_fmac_f32_e32 v114, v70, v70
	v_fmac_f32_e32 v114, v71, v71
	v_fmac_f32_e32 v114, v72, v72
	v_fmac_f32_e32 v114, v73, v73
	v_fmac_f32_e32 v114, v74, v74
	v_fmac_f32_e32 v114, v75, v75
	v_fmac_f32_e32 v114, v76, v76
	v_fmac_f32_e32 v114, v77, v77
	v_fmac_f32_e32 v114, v78, v78
	v_fmac_f32_e32 v114, v79, v79
	v_fmac_f32_e32 v114, v80, v80
	v_fmac_f32_e32 v114, v81, v81
	ds_bpermute_b32 v115, v142, v114
	s_waitcnt lgkmcnt(0)
	v_add_f32_e32 v114, v114, v115
	ds_bpermute_b32 v115, v143, v114
	s_waitcnt lgkmcnt(0)
	v_add_f32_e32 v114, v114, v115
	ds_bpermute_b32 v115, v144, v114
	s_waitcnt lgkmcnt(0)
	v_add_f32_e32 v114, v114, v115
	ds_bpermute_b32 v115, v145, v114
	s_waitcnt lgkmcnt(0)
	v_add_f32_e32 v114, v114, v115
	ds_bpermute_b32 v115, v146, v114
	s_waitcnt lgkmcnt(0)
	v_add_f32_e32 v114, v114, v115
	ds_bpermute_b32 v115, v147, v114
	s_waitcnt lgkmcnt(0)
	v_add_f32_e32 v114, v114, v115
	v_fmamk_f32 v114, v114, 0x3a800000, v124
	v_rsq_f32_e32 v116, v114
	s_nop 0
	v_mul_f32_e32 v118, v116, v196
	v_mul_f32_e32 v66, v66, v118
	v_mul_f32_e32 v119, v116, v197
	v_mul_f32_e32 v67, v67, v119
	v_mul_f32_e32 v120, v116, v198
	v_mul_f32_e32 v68, v68, v120
	v_mul_f32_e32 v121, v116, v199
	v_mul_f32_e32 v69, v69, v121
	global_store_dwordx4 v194, v[66:69], s[50:51] offset:0
	v_mul_f32_e32 v118, v116, v200
	v_mul_f32_e32 v70, v70, v118
	v_mul_f32_e32 v119, v116, v201
	v_mul_f32_e32 v71, v71, v119
	v_mul_f32_e32 v120, v116, v202
	v_mul_f32_e32 v72, v72, v120
	v_mul_f32_e32 v121, v116, v203
	v_mul_f32_e32 v73, v73, v121
	global_store_dwordx4 v194, v[70:73], s[50:51] offset:1024
	v_mul_f32_e32 v118, v116, v204
	v_mul_f32_e32 v74, v74, v118
	v_mul_f32_e32 v119, v116, v205
	v_mul_f32_e32 v75, v75, v119
	v_mul_f32_e32 v120, v116, v206
	v_mul_f32_e32 v76, v76, v120
	v_mul_f32_e32 v121, v116, v207
	v_mul_f32_e32 v77, v77, v121
	global_store_dwordx4 v194, v[74:77], s[50:51] offset:2048
	v_mul_f32_e32 v118, v116, v208
	v_mul_f32_e32 v78, v78, v118
	v_mul_f32_e32 v119, v116, v209
	v_mul_f32_e32 v79, v79, v119
	v_mul_f32_e32 v120, v116, v210
	v_mul_f32_e32 v80, v80, v120
	v_mul_f32_e32 v121, v116, v211
	v_mul_f32_e32 v81, v81, v121
	global_store_dwordx4 v194, v[78:81], s[50:51] offset:3072
	s_add_u32 s8, s52, 0x7000
	s_addc_u32 s9, s53, 0
	s_add_u32 s50, s56, 0x7000
	s_addc_u32 s51, s57, 0
	s_add_u32 s34, s54, 0x3800
	s_addc_u32 s35, s55, 0
	global_load_dwordx2 v[106:107], v188, s[34:35] offset:0
	global_load_dwordx2 v[108:109], v188, s[34:35] offset:512
	global_load_dwordx2 v[110:111], v188, s[34:35] offset:1024
	global_load_dwordx2 v[112:113], v188, s[34:35] offset:1536
	global_load_dwordx4 v[66:69], v194, s[8:9] offset:0 nt
	global_load_dwordx4 v[70:73], v194, s[8:9] offset:1024 nt
	global_load_dwordx4 v[74:77], v194, s[8:9] offset:2048 nt
	global_load_dwordx4 v[78:81], v194, s[8:9] offset:3072 nt
	s_waitcnt vmcnt(36)
	v_lshlrev_b32_e32 v118, 16, v82
	v_and_b32_e32 v119, 0xffff0000, v82
	v_lshlrev_b32_e32 v120, 16, v83
	v_and_b32_e32 v121, 0xffff0000, v83
	v_add_f32_e32 v18, v18, v118
	v_add_f32_e32 v19, v19, v119
	v_add_f32_e32 v20, v20, v120
	v_add_f32_e32 v21, v21, v121
	v_lshlrev_b32_e32 v118, 16, v84
	v_and_b32_e32 v119, 0xffff0000, v84
	v_lshlrev_b32_e32 v120, 16, v85
	v_and_b32_e32 v121, 0xffff0000, v85
	v_add_f32_e32 v22, v22, v118
	v_add_f32_e32 v23, v23, v119
	v_add_f32_e32 v24, v24, v120
	v_add_f32_e32 v25, v25, v121
	v_lshlrev_b32_e32 v118, 16, v86
	v_and_b32_e32 v119, 0xffff0000, v86
	v_lshlrev_b32_e32 v120, 16, v87
	v_and_b32_e32 v121, 0xffff0000, v87
	v_add_f32_e32 v26, v26, v118
	v_add_f32_e32 v27, v27, v119
	v_add_f32_e32 v28, v28, v120
	v_add_f32_e32 v29, v29, v121
	v_lshlrev_b32_e32 v118, 16, v88
	v_and_b32_e32 v119, 0xffff0000, v88
	v_lshlrev_b32_e32 v120, 16, v89
	v_and_b32_e32 v121, 0xffff0000, v89
	v_add_f32_e32 v30, v30, v118
	v_add_f32_e32 v31, v31, v119
	v_add_f32_e32 v32, v32, v120
	v_add_f32_e32 v33, v33, v121
	v_mul_f32_e32 v114, v18, v18
	v_fmac_f32_e32 v114, v19, v19
	v_fmac_f32_e32 v114, v20, v20
	v_fmac_f32_e32 v114, v21, v21
	v_fmac_f32_e32 v114, v22, v22
	v_fmac_f32_e32 v114, v23, v23
	v_fmac_f32_e32 v114, v24, v24
	v_fmac_f32_e32 v114, v25, v25
	v_fmac_f32_e32 v114, v26, v26
	v_fmac_f32_e32 v114, v27, v27
	v_fmac_f32_e32 v114, v28, v28
	v_fmac_f32_e32 v114, v29, v29
	v_fmac_f32_e32 v114, v30, v30
	v_fmac_f32_e32 v114, v31, v31
	v_fmac_f32_e32 v114, v32, v32
	v_fmac_f32_e32 v114, v33, v33
	ds_bpermute_b32 v115, v142, v114
	s_waitcnt lgkmcnt(0)
	v_add_f32_e32 v114, v114, v115
	ds_bpermute_b32 v115, v143, v114
	s_waitcnt lgkmcnt(0)
	v_add_f32_e32 v114, v114, v115
	ds_bpermute_b32 v115, v144, v114
	s_waitcnt lgkmcnt(0)
	v_add_f32_e32 v114, v114, v115
	ds_bpermute_b32 v115, v145, v114
	s_waitcnt lgkmcnt(0)
	v_add_f32_e32 v114, v114, v115
	ds_bpermute_b32 v115, v146, v114
	s_waitcnt lgkmcnt(0)
	v_add_f32_e32 v114, v114, v115
	ds_bpermute_b32 v115, v147, v114
	s_waitcnt lgkmcnt(0)
	v_add_f32_e32 v114, v114, v115
	v_fmamk_f32 v114, v114, 0x3a800000, v124
	v_rsq_f32_e32 v116, v114
	s_nop 0
	v_mul_f32_e32 v118, v116, v196
	v_mul_f32_e32 v18, v18, v118
	v_mul_f32_e32 v119, v116, v197
	v_mul_f32_e32 v19, v19, v119
	v_mul_f32_e32 v120, v116, v198
	v_mul_f32_e32 v20, v20, v120
	v_mul_f32_e32 v121, v116, v199
	v_mul_f32_e32 v21, v21, v121
	global_store_dwordx4 v194, v[18:21], s[44:45] offset:0
	v_mul_f32_e32 v118, v116, v200
	v_mul_f32_e32 v22, v22, v118
	v_mul_f32_e32 v119, v116, v201
	v_mul_f32_e32 v23, v23, v119
	v_mul_f32_e32 v120, v116, v202
	v_mul_f32_e32 v24, v24, v120
	v_mul_f32_e32 v121, v116, v203
	v_mul_f32_e32 v25, v25, v121
	global_store_dwordx4 v194, v[22:25], s[44:45] offset:1024
	v_mul_f32_e32 v118, v116, v204
	v_mul_f32_e32 v26, v26, v118
	v_mul_f32_e32 v119, v116, v205
	v_mul_f32_e32 v27, v27, v119
	v_mul_f32_e32 v120, v116, v206
	v_mul_f32_e32 v28, v28, v120
	v_mul_f32_e32 v121, v116, v207
	v_mul_f32_e32 v29, v29, v121
	global_store_dwordx4 v194, v[26:29], s[44:45] offset:2048
	v_mul_f32_e32 v118, v116, v208
	v_mul_f32_e32 v30, v30, v118
	v_mul_f32_e32 v119, v116, v209
	v_mul_f32_e32 v31, v31, v119
	v_mul_f32_e32 v120, v116, v210
	v_mul_f32_e32 v32, v32, v120
	v_mul_f32_e32 v121, v116, v211
	v_mul_f32_e32 v33, v33, v121
	global_store_dwordx4 v194, v[30:33], s[44:45] offset:3072
	s_waitcnt vmcnt(28)
	v_lshlrev_b32_e32 v118, 16, v90
	v_and_b32_e32 v119, 0xffff0000, v90
	v_lshlrev_b32_e32 v120, 16, v91
	v_and_b32_e32 v121, 0xffff0000, v91
	v_add_f32_e32 v34, v34, v118
	v_add_f32_e32 v35, v35, v119
	v_add_f32_e32 v36, v36, v120
	v_add_f32_e32 v37, v37, v121
	v_lshlrev_b32_e32 v118, 16, v92
	v_and_b32_e32 v119, 0xffff0000, v92
	v_lshlrev_b32_e32 v120, 16, v93
	v_and_b32_e32 v121, 0xffff0000, v93
	v_add_f32_e32 v38, v38, v118
	v_add_f32_e32 v39, v39, v119
	v_add_f32_e32 v40, v40, v120
	v_add_f32_e32 v41, v41, v121
	v_lshlrev_b32_e32 v118, 16, v94
	v_and_b32_e32 v119, 0xffff0000, v94
	v_lshlrev_b32_e32 v120, 16, v95
	v_and_b32_e32 v121, 0xffff0000, v95
	v_add_f32_e32 v42, v42, v118
	v_add_f32_e32 v43, v43, v119
	v_add_f32_e32 v44, v44, v120
	v_add_f32_e32 v45, v45, v121
	v_lshlrev_b32_e32 v118, 16, v96
	v_and_b32_e32 v119, 0xffff0000, v96
	v_lshlrev_b32_e32 v120, 16, v97
	v_and_b32_e32 v121, 0xffff0000, v97
	v_add_f32_e32 v46, v46, v118
	v_add_f32_e32 v47, v47, v119
	v_add_f32_e32 v48, v48, v120
	v_add_f32_e32 v49, v49, v121
	v_mul_f32_e32 v114, v34, v34
	v_fmac_f32_e32 v114, v35, v35
	v_fmac_f32_e32 v114, v36, v36
	v_fmac_f32_e32 v114, v37, v37
	v_fmac_f32_e32 v114, v38, v38
	v_fmac_f32_e32 v114, v39, v39
	v_fmac_f32_e32 v114, v40, v40
	v_fmac_f32_e32 v114, v41, v41
	v_fmac_f32_e32 v114, v42, v42
	v_fmac_f32_e32 v114, v43, v43
	v_fmac_f32_e32 v114, v44, v44
	v_fmac_f32_e32 v114, v45, v45
	v_fmac_f32_e32 v114, v46, v46
	v_fmac_f32_e32 v114, v47, v47
	v_fmac_f32_e32 v114, v48, v48
	v_fmac_f32_e32 v114, v49, v49
	ds_bpermute_b32 v115, v142, v114
	s_waitcnt lgkmcnt(0)
	v_add_f32_e32 v114, v114, v115
	ds_bpermute_b32 v115, v143, v114
	s_waitcnt lgkmcnt(0)
	v_add_f32_e32 v114, v114, v115
	ds_bpermute_b32 v115, v144, v114
	s_waitcnt lgkmcnt(0)
	v_add_f32_e32 v114, v114, v115
	ds_bpermute_b32 v115, v145, v114
	s_waitcnt lgkmcnt(0)
	v_add_f32_e32 v114, v114, v115
	ds_bpermute_b32 v115, v146, v114
	s_waitcnt lgkmcnt(0)
	v_add_f32_e32 v114, v114, v115
	ds_bpermute_b32 v115, v147, v114
	s_waitcnt lgkmcnt(0)
	v_add_f32_e32 v114, v114, v115
	v_fmamk_f32 v114, v114, 0x3a800000, v124
	v_rsq_f32_e32 v116, v114
	s_nop 0
	v_mul_f32_e32 v118, v116, v196
	v_mul_f32_e32 v34, v34, v118
	v_mul_f32_e32 v119, v116, v197
	v_mul_f32_e32 v35, v35, v119
	v_mul_f32_e32 v120, v116, v198
	v_mul_f32_e32 v36, v36, v120
	v_mul_f32_e32 v121, v116, v199
	v_mul_f32_e32 v37, v37, v121
	global_store_dwordx4 v194, v[34:37], s[46:47] offset:0
	v_mul_f32_e32 v118, v116, v200
	v_mul_f32_e32 v38, v38, v118
	v_mul_f32_e32 v119, v116, v201
	v_mul_f32_e32 v39, v39, v119
	v_mul_f32_e32 v120, v116, v202
	v_mul_f32_e32 v40, v40, v120
	v_mul_f32_e32 v121, v116, v203
	v_mul_f32_e32 v41, v41, v121
	global_store_dwordx4 v194, v[38:41], s[46:47] offset:1024
	v_mul_f32_e32 v118, v116, v204
	v_mul_f32_e32 v42, v42, v118
	v_mul_f32_e32 v119, v116, v205
	v_mul_f32_e32 v43, v43, v119
	v_mul_f32_e32 v120, v116, v206
	v_mul_f32_e32 v44, v44, v120
	v_mul_f32_e32 v121, v116, v207
	v_mul_f32_e32 v45, v45, v121
	global_store_dwordx4 v194, v[42:45], s[46:47] offset:2048
	v_mul_f32_e32 v118, v116, v208
	v_mul_f32_e32 v46, v46, v118
	v_mul_f32_e32 v119, v116, v209
	v_mul_f32_e32 v47, v47, v119
	v_mul_f32_e32 v120, v116, v210
	v_mul_f32_e32 v48, v48, v120
	v_mul_f32_e32 v121, v116, v211
	v_mul_f32_e32 v49, v49, v121
	global_store_dwordx4 v194, v[46:49], s[46:47] offset:3072
	s_waitcnt vmcnt(20)
	v_lshlrev_b32_e32 v118, 16, v98
	v_and_b32_e32 v119, 0xffff0000, v98
	v_lshlrev_b32_e32 v120, 16, v99
	v_and_b32_e32 v121, 0xffff0000, v99
	v_add_f32_e32 v50, v50, v118
	v_add_f32_e32 v51, v51, v119
	v_add_f32_e32 v52, v52, v120
	v_add_f32_e32 v53, v53, v121
	v_lshlrev_b32_e32 v118, 16, v100
	v_and_b32_e32 v119, 0xffff0000, v100
	v_lshlrev_b32_e32 v120, 16, v101
	v_and_b32_e32 v121, 0xffff0000, v101
	v_add_f32_e32 v54, v54, v118
	v_add_f32_e32 v55, v55, v119
	v_add_f32_e32 v56, v56, v120
	v_add_f32_e32 v57, v57, v121
	v_lshlrev_b32_e32 v118, 16, v102
	v_and_b32_e32 v119, 0xffff0000, v102
	v_lshlrev_b32_e32 v120, 16, v103
	v_and_b32_e32 v121, 0xffff0000, v103
	v_add_f32_e32 v58, v58, v118
	v_add_f32_e32 v59, v59, v119
	v_add_f32_e32 v60, v60, v120
	v_add_f32_e32 v61, v61, v121
	v_lshlrev_b32_e32 v118, 16, v104
	v_and_b32_e32 v119, 0xffff0000, v104
	v_lshlrev_b32_e32 v120, 16, v105
	v_and_b32_e32 v121, 0xffff0000, v105
	v_add_f32_e32 v62, v62, v118
	v_add_f32_e32 v63, v63, v119
	v_add_f32_e32 v64, v64, v120
	v_add_f32_e32 v65, v65, v121
	v_mul_f32_e32 v114, v50, v50
	v_fmac_f32_e32 v114, v51, v51
	v_fmac_f32_e32 v114, v52, v52
	v_fmac_f32_e32 v114, v53, v53
	v_fmac_f32_e32 v114, v54, v54
	v_fmac_f32_e32 v114, v55, v55
	v_fmac_f32_e32 v114, v56, v56
	v_fmac_f32_e32 v114, v57, v57
	v_fmac_f32_e32 v114, v58, v58
	v_fmac_f32_e32 v114, v59, v59
	v_fmac_f32_e32 v114, v60, v60
	v_fmac_f32_e32 v114, v61, v61
	v_fmac_f32_e32 v114, v62, v62
	v_fmac_f32_e32 v114, v63, v63
	v_fmac_f32_e32 v114, v64, v64
	v_fmac_f32_e32 v114, v65, v65
	ds_bpermute_b32 v115, v142, v114
	s_waitcnt lgkmcnt(0)
	v_add_f32_e32 v114, v114, v115
	ds_bpermute_b32 v115, v143, v114
	s_waitcnt lgkmcnt(0)
	v_add_f32_e32 v114, v114, v115
	ds_bpermute_b32 v115, v144, v114
	s_waitcnt lgkmcnt(0)
	v_add_f32_e32 v114, v114, v115
	ds_bpermute_b32 v115, v145, v114
	s_waitcnt lgkmcnt(0)
	v_add_f32_e32 v114, v114, v115
	ds_bpermute_b32 v115, v146, v114
	s_waitcnt lgkmcnt(0)
	v_add_f32_e32 v114, v114, v115
	ds_bpermute_b32 v115, v147, v114
	s_waitcnt lgkmcnt(0)
	v_add_f32_e32 v114, v114, v115
	v_fmamk_f32 v114, v114, 0x3a800000, v124
	v_rsq_f32_e32 v116, v114
	s_nop 0
	v_mul_f32_e32 v118, v116, v196
	v_mul_f32_e32 v50, v50, v118
	v_mul_f32_e32 v119, v116, v197
	v_mul_f32_e32 v51, v51, v119
	v_mul_f32_e32 v120, v116, v198
	v_mul_f32_e32 v52, v52, v120
	v_mul_f32_e32 v121, v116, v199
	v_mul_f32_e32 v53, v53, v121
	global_store_dwordx4 v194, v[50:53], s[48:49] offset:0
	v_mul_f32_e32 v118, v116, v200
	v_mul_f32_e32 v54, v54, v118
	v_mul_f32_e32 v119, v116, v201
	v_mul_f32_e32 v55, v55, v119
	v_mul_f32_e32 v120, v116, v202
	v_mul_f32_e32 v56, v56, v120
	v_mul_f32_e32 v121, v116, v203
	v_mul_f32_e32 v57, v57, v121
	global_store_dwordx4 v194, v[54:57], s[48:49] offset:1024
	v_mul_f32_e32 v118, v116, v204
	v_mul_f32_e32 v58, v58, v118
	v_mul_f32_e32 v119, v116, v205
	v_mul_f32_e32 v59, v59, v119
	v_mul_f32_e32 v120, v116, v206
	v_mul_f32_e32 v60, v60, v120
	v_mul_f32_e32 v121, v116, v207
	v_mul_f32_e32 v61, v61, v121
	global_store_dwordx4 v194, v[58:61], s[48:49] offset:2048
	v_mul_f32_e32 v118, v116, v208
	v_mul_f32_e32 v62, v62, v118
	v_mul_f32_e32 v119, v116, v209
	v_mul_f32_e32 v63, v63, v119
	v_mul_f32_e32 v120, v116, v210
	v_mul_f32_e32 v64, v64, v120
	v_mul_f32_e32 v121, v116, v211
	v_mul_f32_e32 v65, v65, v121
	global_store_dwordx4 v194, v[62:65], s[48:49] offset:3072
	s_waitcnt vmcnt(12)
	v_lshlrev_b32_e32 v118, 16, v106
	v_and_b32_e32 v119, 0xffff0000, v106
	v_lshlrev_b32_e32 v120, 16, v107
	v_and_b32_e32 v121, 0xffff0000, v107
	v_add_f32_e32 v66, v66, v118
	v_add_f32_e32 v67, v67, v119
	v_add_f32_e32 v68, v68, v120
	v_add_f32_e32 v69, v69, v121
	v_lshlrev_b32_e32 v118, 16, v108
	v_and_b32_e32 v119, 0xffff0000, v108
	v_lshlrev_b32_e32 v120, 16, v109
	v_and_b32_e32 v121, 0xffff0000, v109
	v_add_f32_e32 v70, v70, v118
	v_add_f32_e32 v71, v71, v119
	v_add_f32_e32 v72, v72, v120
	v_add_f32_e32 v73, v73, v121
	v_lshlrev_b32_e32 v118, 16, v110
	v_and_b32_e32 v119, 0xffff0000, v110
	v_lshlrev_b32_e32 v120, 16, v111
	v_and_b32_e32 v121, 0xffff0000, v111
	v_add_f32_e32 v74, v74, v118
	v_add_f32_e32 v75, v75, v119
	v_add_f32_e32 v76, v76, v120
	v_add_f32_e32 v77, v77, v121
	v_lshlrev_b32_e32 v118, 16, v112
	v_and_b32_e32 v119, 0xffff0000, v112
	v_lshlrev_b32_e32 v120, 16, v113
	v_and_b32_e32 v121, 0xffff0000, v113
	v_add_f32_e32 v78, v78, v118
	v_add_f32_e32 v79, v79, v119
	v_add_f32_e32 v80, v80, v120
	v_add_f32_e32 v81, v81, v121
	v_mul_f32_e32 v114, v66, v66
	v_fmac_f32_e32 v114, v67, v67
	v_fmac_f32_e32 v114, v68, v68
	v_fmac_f32_e32 v114, v69, v69
	v_fmac_f32_e32 v114, v70, v70
	v_fmac_f32_e32 v114, v71, v71
	v_fmac_f32_e32 v114, v72, v72
	v_fmac_f32_e32 v114, v73, v73
	v_fmac_f32_e32 v114, v74, v74
	v_fmac_f32_e32 v114, v75, v75
	v_fmac_f32_e32 v114, v76, v76
	v_fmac_f32_e32 v114, v77, v77
	v_fmac_f32_e32 v114, v78, v78
	v_fmac_f32_e32 v114, v79, v79
	v_fmac_f32_e32 v114, v80, v80
	v_fmac_f32_e32 v114, v81, v81
	ds_bpermute_b32 v115, v142, v114
	s_waitcnt lgkmcnt(0)
	v_add_f32_e32 v114, v114, v115
	ds_bpermute_b32 v115, v143, v114
	s_waitcnt lgkmcnt(0)
	v_add_f32_e32 v114, v114, v115
	ds_bpermute_b32 v115, v144, v114
	s_waitcnt lgkmcnt(0)
	v_add_f32_e32 v114, v114, v115
	ds_bpermute_b32 v115, v145, v114
	s_waitcnt lgkmcnt(0)
	v_add_f32_e32 v114, v114, v115
	ds_bpermute_b32 v115, v146, v114
	s_waitcnt lgkmcnt(0)
	v_add_f32_e32 v114, v114, v115
	ds_bpermute_b32 v115, v147, v114
	s_waitcnt lgkmcnt(0)
	v_add_f32_e32 v114, v114, v115
	v_fmamk_f32 v114, v114, 0x3a800000, v124
	v_rsq_f32_e32 v116, v114
	s_nop 0
	v_mul_f32_e32 v118, v116, v196
	v_mul_f32_e32 v66, v66, v118
	v_mul_f32_e32 v119, v116, v197
	v_mul_f32_e32 v67, v67, v119
	v_mul_f32_e32 v120, v116, v198
	v_mul_f32_e32 v68, v68, v120
	v_mul_f32_e32 v121, v116, v199
	v_mul_f32_e32 v69, v69, v121
	global_store_dwordx4 v194, v[66:69], s[50:51] offset:0
	v_mul_f32_e32 v118, v116, v200
	v_mul_f32_e32 v70, v70, v118
	v_mul_f32_e32 v119, v116, v201
	v_mul_f32_e32 v71, v71, v119
	v_mul_f32_e32 v120, v116, v202
	v_mul_f32_e32 v72, v72, v120
	v_mul_f32_e32 v121, v116, v203
	v_mul_f32_e32 v73, v73, v121
	global_store_dwordx4 v194, v[70:73], s[50:51] offset:1024
	v_mul_f32_e32 v118, v116, v204
	v_mul_f32_e32 v74, v74, v118
	v_mul_f32_e32 v119, v116, v205
	v_mul_f32_e32 v75, v75, v119
	v_mul_f32_e32 v120, v116, v206
	v_mul_f32_e32 v76, v76, v120
	v_mul_f32_e32 v121, v116, v207
	v_mul_f32_e32 v77, v77, v121
	global_store_dwordx4 v194, v[74:77], s[50:51] offset:2048
	v_mul_f32_e32 v118, v116, v208
	v_mul_f32_e32 v78, v78, v118
	v_mul_f32_e32 v119, v116, v209
	v_mul_f32_e32 v79, v79, v119
	v_mul_f32_e32 v120, v116, v210
	v_mul_f32_e32 v80, v80, v120
	v_mul_f32_e32 v121, v116, v211
	v_mul_f32_e32 v81, v81, v121
	global_store_dwordx4 v194, v[78:81], s[50:51] offset:3072
	s_add_i32 s83, s83, 1
	s_branch .Lp45_loop
